# GEMM phase prologue: K-tile 1 staging loads issued together with K-tile 0's (ahead of the first wait/barrier) instead of one memory round trip later
# baseline (speedup 1.0000x reference)
.LBB0_299:
	v_bfe_u32 v1, v0, 4, 2
	v_and_b32_e32 v2, 15, v0
	v_lshlrev_b32_e32 v4, 4, v1
	v_lshlrev_b32_e32 v0, 2, v0
	s_and_b32 s54, s22, 3
	s_lshr_b32 s22, s3, 6
	v_lshl_or_b32 v249, s23, 6, v2
	v_lshl_or_b32 v2, v2, 6, v4
	s_lshl_b32 s3, s23, 13
	v_and_b32_e32 v0, 32, v0
	v_bitop3_b32 v4, v2, s3, v0 bitop3:0xde
	s_lshl_b32 s3, s54, 12
	s_add_u32 s40, s42, 0x80
	v_bitop3_b32 v0, v2, s3, v0 bitop3:0xde
	s_addc_u32 s41, s43, 0
	s_add_i32 s23, s11, 0x18000
	s_mov_b32 s3, m0
	s_mov_b32 m0, s23
	s_nop 0
	global_load_lds_dwordx4 v246, s[40:41]
	s_mov_b32 m0, s3
	s_add_i32 s30, s11, 0x1a000
	s_mov_b32 s3, m0
	s_mov_b32 m0, s30
	s_nop 0
	global_load_lds_dwordx4 v248, s[40:41]
	s_mov_b32 m0, s3
	s_add_u32 s40, s72, 0x80
	s_addc_u32 s41, s73, 0
	s_add_i32 s47, s11, 0x8000
	s_add_i32 s50, s11, 0xa000
	s_mov_b32 s3, m0
	s_mov_b32 m0, s47
	s_nop 0
	global_load_lds_dwordx4 v245, s[40:41]
	s_mov_b32 m0, s3
	s_add_u32 s36, s36, 0x80
	s_mov_b32 s3, m0
	s_mov_b32 m0, s50
	s_nop 0
	global_load_lds_dwordx4 v247, s[40:41]
	s_mov_b32 m0, s3
	s_addc_u32 s37, s37, 0
	s_add_i32 s52, s11, 0x1c000
	s_add_i32 s53, s11, 0x1e000
	s_add_i32 s57, s22, -2
	s_add_i32 s65, s11, 0xc000
	s_mov_b32 s3, m0
	s_mov_b32 m0, s52
	s_nop 0
	global_load_lds_dwordx4 v246, s[36:37]
	s_mov_b32 m0, s3
	s_cmpk_lt_u32 s38, 0x100
	s_mov_b32 s3, m0
	s_mov_b32 m0, s53
	s_nop 0
	global_load_lds_dwordx4 v248, s[36:37]
	s_mov_b32 m0, s3
	s_cselect_b64 s[36:37], -1, 0
	s_ashr_i32 s67, s60, 31
	s_lshr_b32 s40, s67, 29
	s_add_i32 s40, s60, s40
	s_ashr_i32 s41, s40, 3
	s_and_b32 s40, s40, -8
	s_lshl_b32 s48, s41, 2
	s_sub_i32 s40, s60, s40
	s_and_b32 s48, s48, -8
	s_add_i32 s48, s48, s40
	s_add_i32 s66, s11, 0xe000
	s_ashr_i32 s40, s48, 31
	v_readlane_b32 s49, v254, 5
	s_waitcnt vmcnt(8)
	s_barrier
	s_waitcnt vmcnt(6)
	s_add_u32 s48, s49, s48
	v_readlane_b32 s49, v254, 12
	v_lshlrev_b32_e32 v3, 3, v1
	s_mul_hi_i32 s49, s49, s56
	v_lshl_or_b32 v250, s54, 5, v3
	s_mov_b32 s3, 0
	v_cmp_eq_u32_e64 s[38:39], 0, v1
	s_addc_u32 s49, s49, s40
	s_and_b32 s82, s41, 1
	s_lshl_b32 s84, s54, 2
	v_add_u32_e32 v251, 0, v0
	v_add_u32_e32 v252, 0, v4
	s_barrier
	s_branch .LBB0_302

.LBB0_402:
	v_and_b32_e32 v1, 15, v0
	v_bfe_u32 v0, v0, 4, 2
	v_lshlrev_b32_e32 v2, 4, v0
	v_lshlrev_b32_e32 v4, 2, v1
	s_and_b32 s17, s9, 3
	v_lshl_or_b32 v3, v1, 6, v2
	s_lshl_b32 s9, s16, 13
	v_and_b32_e32 v5, 32, v4
	v_bitop3_b32 v6, v3, s9, v5 bitop3:0xde
	s_lshl_b32 s94, s17, 5
	s_lshl_b32 s9, s17, 12
	s_add_u32 s18, s44, 0x80
	v_bitop3_b32 v3, v3, s9, v5 bitop3:0xde
	s_addc_u32 s19, s45, 0
	s_add_i32 s95, s51, 0x18000
	s_mov_b32 s9, m0
	s_mov_b32 m0, s95
	s_nop 0
	global_load_lds_dwordx4 v196, s[18:19]
	s_mov_b32 m0, s9
	s_add_i32 s96, s51, 0x1a000
	s_mov_b32 s9, m0
	s_mov_b32 m0, s96
	s_nop 0
	global_load_lds_dwordx4 v198, s[18:19]
	s_mov_b32 m0, s9
	s_add_u32 s18, s46, 0x80
	s_addc_u32 s19, s47, 0
	s_add_i32 s97, s51, 0x8000
	s_mov_b32 s9, m0
	s_mov_b32 m0, s97
	s_nop 0
	global_load_lds_dwordx4 v195, s[18:19]
	s_mov_b32 m0, s9
	s_add_i32 s9, s51, 0xa000
	s_mov_b32 s20, m0
	s_mov_b32 m0, s9
	s_nop 0
	global_load_lds_dwordx4 v197, s[18:19]
	s_mov_b32 m0, s20
	s_add_u32 s18, s44, 0x40080
	s_addc_u32 s19, s45, 0
	s_add_i32 s65, s51, 0x1c000
	s_mov_b32 s20, m0
	s_mov_b32 m0, s65
	s_nop 0
	global_load_lds_dwordx4 v196, s[18:19]
	s_mov_b32 m0, s20
	s_add_i32 s50, s51, 0x1e000
	s_add_i32 s30, s51, 0xc000
	s_mov_b32 s20, m0
	s_mov_b32 m0, s50
	s_nop 0
	global_load_lds_dwordx4 v198, s[18:19]
	s_mov_b32 m0, s20
	s_cmpk_lt_u32 s14, 0x100
	s_cselect_b64 s[20:21], -1, 0
	s_and_b32 s14, s14, 0xffffff00
	s_lshl_b32 s18, s17, 6
	s_or_b32 s14, s18, s14
	v_or3_b32 v200, s14, v2, v1
	s_movk_i32 s14, 0x100
	v_cmp_gt_i32_e64 s[18:19], s14, v200
	s_lshl_b32 s14, s16, 8
	v_lshl_or_b32 v199, s16, 6, v1
	v_writelane_b32 v255, s18, 29
	s_waitcnt vmcnt(8)
	s_barrier
	s_waitcnt vmcnt(6)
	v_lshlrev_b32_e32 v204, 5, v199
	v_lshlrev_b32_e32 v194, 3, v0
	v_writelane_b32 v255, s19, 30
	v_readlane_b32 s18, v254, 44
	s_add_i32 s14, s18, s14
	v_add_u32_e32 v202, s14, v4
	v_lshl_add_u32 v201, v200, 2, s18
	s_lshl_b32 s14, s17, 2
	v_readlane_b32 s18, v254, 45
	s_add_i32 s16, s18, s14
	v_writelane_b32 v255, s16, 27
	s_and_b32 s16, s94, 32
	v_cmp_eq_u32_e64 s[42:43], 0, v0
	s_xor_b32 s17, s17, 1
	v_add_u32_e32 v0, s18, v204
	s_and_b32 s98, s3, 1
	s_lshl_b32 s3, s16, 2
	s_mov_b32 s69, 0
	v_cmp_eq_u32_e64 s[40:41], 0, v200
	v_or_b32_e32 v203, s94, v194
	v_add_u32_e32 v205, s14, v0
	v_lshl_add_u32 v206, s17, 2, v0
	s_add_i32 s14, s51, 0xe000
	v_writelane_b32 v255, s3, 39
	v_lshlrev_b32_e32 v207, 2, v194
	v_add_u32_e32 v208, 0, v3
	v_add_u32_e32 v209, 0, v6
	s_barrier
	s_branch .LBB0_405
